# att20 = att18 + LDS sub-LN gains (no store-ack ladder) + next unit-map's V0 tile prefetched behind the drain (extra barrier); prefetched prologue issues no memory op and leaves the 8 row stores in fli
# speedup vs baseline: 1.0178x; 1.0178x over previous
.LBB0_278:
	v_and_b32_e32 v0, 63, v244
	v_lshlrev_b32_e32 v0, 2, v0
	global_load_dword v2, v0, s[72:73]
	global_load_dword v3, v0, s[74:75]
	global_load_dword v4, v0, s[76:77]
	s_nop 0
	global_load_dword v0, v0, s[78:79]
	v_mbcnt_hi_u32_b32 v5, -1, v145
	v_and_b32_e32 v6, 64, v5
	v_xor_b32_e32 v7, 1, v5
	v_add_u32_e32 v6, 64, v6
	v_cmp_lt_i32_e32 vcc, v7, v6
	v_xor_b32_e32 v8, 2, v5
	v_xor_b32_e32 v9, 4, v5
	v_cndmask_b32_e32 v7, v5, v7, vcc
	v_lshlrev_b32_e32 v232, 2, v7
	v_cmp_lt_i32_e32 vcc, v8, v6
	v_xor_b32_e32 v10, 8, v5
	v_xor_b32_e32 v11, 16, v5
	v_cndmask_b32_e32 v8, v5, v8, vcc
	v_lshlrev_b32_e32 v8, 2, v8
	v_cmp_lt_i32_e32 vcc, v9, v6
	v_xor_b32_e32 v12, 32, v5
	s_add_u32 s94, s22, 0xb000000
	v_cndmask_b32_e32 v9, v5, v9, vcc
	v_cmp_lt_i32_e32 vcc, v10, v6
	s_addc_u32 s95, s23, 0
	s_add_u32 s0, s22, 0xf000000
	v_cndmask_b32_e32 v10, v5, v10, vcc
	v_cmp_lt_i32_e32 vcc, v11, v6
	s_addc_u32 s1, s23, 0
	v_writelane_b32 v254, s0, 35
	s_mov_b32 s7, 0
	v_mov_b32_e32 v1, 0
	v_writelane_b32 v254, s1, 36
	s_add_u32 s0, s22, 0x13000000
	s_addc_u32 s1, s23, 0
	s_add_u32 s86, s20, 0x4000000
	v_writelane_b32 v254, s0, 37
	s_addc_u32 s87, s21, 0
	s_cmpk_lg_i32 s84, 0x100
	v_writelane_b32 v254, s1, 38
	s_cselect_b64 s[96:97], -1, 0
	s_and_b32 s0, s2, 7
	v_writelane_b32 v254, s2, 39
	s_ashr_i32 s1, s2, 3
	v_writelane_b32 v254, s1, 40
	s_xor_b32 s1, s0, 15
	v_writelane_b32 v254, s1, 41
	s_or_b32 s1, s0, 16
	v_writelane_b32 v254, s1, 42
	v_writelane_b32 v254, s0, 43
	s_xor_b32 s0, s0, 31
	v_writelane_b32 v254, s0, 44
	v_writelane_b32 v254, s16, 45
	s_mov_b64 s[8:9], 0x20000
	s_mov_b64 s[10:11], 0x40000
	s_mov_b64 s[12:13], 0x60000
	s_mov_b64 s[14:15], 0x80000
	s_mov_b64 s[42:43], 0x13040000
	s_mov_b64 s[48:49], 0x13040080
	s_mov_b32 s25, 0x41000000
	v_mov_b32_e32 v230, 0x3727c5ac
	v_mov_b32_e32 v231, 0xff800000
	s_mov_b32 s27, 0
	v_writelane_b32 v254, s40, 46
	s_waitcnt vmcnt(2)
	v_mul_f32_e32 v7, v2, v3
	ds_bpermute_b32 v7, v232, v7
	s_waitcnt vmcnt(0)
	v_mul_f32_e32 v13, v4, v0
	ds_bpermute_b32 v13, v232, v13
	v_writelane_b32 v254, s41, 47
	s_waitcnt lgkmcnt(1)
	v_fmac_f32_e32 v7, v2, v3
	v_cndmask_b32_e32 v3, v5, v11, vcc
	s_waitcnt lgkmcnt(0)
	v_fmac_f32_e32 v13, v4, v0
	ds_bpermute_b32 v0, v8, v7
	ds_bpermute_b32 v2, v8, v13
	v_lshlrev_b32_e32 v4, 2, v9
	v_cmp_lt_i32_e32 vcc, v12, v6
	v_lshlrev_b32_e32 v6, 2, v10
	s_waitcnt lgkmcnt(1)
	v_add_f32_e32 v0, v7, v0
	s_waitcnt lgkmcnt(0)
	v_add_f32_e32 v2, v13, v2
	ds_bpermute_b32 v7, v4, v0
	ds_bpermute_b32 v4, v4, v2
	v_lshlrev_b32_e32 v245, 2, v3
	v_cndmask_b32_e32 v5, v5, v12, vcc
	v_lshlrev_b32_e32 v246, 2, v5
	s_waitcnt lgkmcnt(1)
	v_add_f32_e32 v0, v0, v7
	s_waitcnt lgkmcnt(0)
	v_add_f32_e32 v2, v2, v4
	ds_bpermute_b32 v4, v6, v0
	ds_bpermute_b32 v6, v6, v2
	s_waitcnt lgkmcnt(1)
	v_add_f32_e32 v0, v0, v4
	s_waitcnt lgkmcnt(0)
	v_add_f32_e32 v2, v2, v6
	ds_bpermute_b32 v3, v245, v0
	ds_bpermute_b32 v4, v245, v2
	s_waitcnt lgkmcnt(1)
	v_add_f32_e32 v0, v0, v3
	s_waitcnt lgkmcnt(0)
	v_add_f32_e32 v2, v2, v4
	ds_bpermute_b32 v3, v246, v0
	ds_bpermute_b32 v4, v246, v2
	s_waitcnt lgkmcnt(1)
	v_add_f32_e32 v0, v0, v3
	s_waitcnt lgkmcnt(0)
	v_add_f32_e32 v2, v2, v4
	v_mul_f32_e32 v0, 0x3fb8aa3b, v0
	v_mul_f32_e32 v2, 0x3fb8aa3b, v2
	v_exp_f32_e32 v0, v0
	v_exp_f32_e32 v2, v2
	s_nop 0
	v_sub_f32_e32 v0, v0, v2
	v_add_f32_e32 v233, 0x3e4ccccd, v0
	s_mov_b32 s100, 0
	v_and_b32_e32 v208, 31, v244
	v_lshlrev_b32_e32 v208, 4, v208
	global_load_dwordx4 v[204:207], v208, s[80:81]
	v_lshrrev_b32_e32 v209, 6, v244
	v_lshl_add_u32 v208, v209, 9, v208
	v_add_u32_e32 v208, 0x23000, v208
	s_waitcnt vmcnt(0)
	ds_write_b128 v208, v[204:207]
	s_branch .LBB0_281

.Lkp_skip0:
	v_and_b32_e32 v236, 31, v234
	v_lshl_add_u64 v[34:35], v[2:3], 0, v[0:1]
	s_add_i32 s47, s46, 0x6000
	s_cmp_lg_u32 s100, 0
	s_cbranch_scc1 .Lvp_skipa
	s_mov_b32 s1, m0
	s_mov_b32 m0, s47
	s_nop 0
	global_load_lds_dwordx4 v[34:35], off
	s_mov_b32 m0, s1
.Lvp_skipa:
	s_mov_b64 s[18:19], 0x80
	v_bfe_u32 v252, v234, 5, 1
	v_lshl_add_u64 v[2:3], v[34:35], 0, s[18:19]
	s_add_i32 s1, s46, 0x8000
	s_cmp_lg_u32 s100, 0
	s_cbranch_scc1 .Lvp_skipb
	s_mov_b32 s6, m0
	s_mov_b32 m0, s1
	s_nop 0
	global_load_lds_dwordx4 v[2:3], off
	s_mov_b32 m0, s6
.Lvp_skipb:
	v_lshlrev_b32_e32 v0, 11, v236
	v_lshl_add_u64 v[2:3], v[224:225], 0, s[8:9]
	s_add_i32 s1, s46, 0x2000
	s_cmp_lg_u32 s100, 0
	s_cbranch_scc1 .Lkp_skip1
	s_mov_b32 s6, m0
	s_mov_b32 m0, s1
	s_nop 0
	global_load_lds_dwordx4 v[2:3], off
	s_mov_b32 m0, s6

.Lqp_wb:
	s_cmp_eq_u32 s100, 2
	s_cbranch_scc1 .Lqp_wb8
	s_waitcnt vmcnt(0) lgkmcnt(0)
	s_branch .Lqp_wb2
.Lqp_wb8:
	s_waitcnt vmcnt(8) lgkmcnt(0)

.Lqp_nomov:
	ds_read_b128 v[36:39], v247
	v_or_b32_e32 v242, s38, v236
	s_andn2_b64 vcc, exec, s[54:55]
	v_lshlrev_b32_e32 v237, 2, v252
	s_waitcnt lgkmcnt(0)
	s_cmp_lg_u32 s100, 0
	s_cbranch_scc1 .Lqp_w3
	s_waitcnt vmcnt(3)
.Lqp_w3:
	v_mfma_f32_32x32x16_bf16 v[18:33], v[36:39], v[188:191], v[2:17]
	ds_read_b128 v[36:39], v247 offset:512
	s_waitcnt lgkmcnt(0)
	v_mfma_f32_32x32x16_bf16 v[2:17], v[36:39], v[188:191], v[2:17]
	ds_read_b128 v[36:39], v247 offset:2048
	s_waitcnt lgkmcnt(0)
	s_cmp_lg_u32 s100, 0
	s_cbranch_scc1 .Lqp_w2
	s_waitcnt vmcnt(2)
.Lqp_w2:
	v_mfma_f32_32x32x16_bf16 v[18:33], v[36:39], v[184:187], v[18:33]
	ds_read_b128 v[36:39], v247 offset:2560
	s_waitcnt lgkmcnt(0)
	v_mfma_f32_32x32x16_bf16 v[2:17], v[36:39], v[184:187], v[2:17]
	ds_read_b128 v[36:39], v247 offset:4096
	s_waitcnt lgkmcnt(0)
	s_cmp_lg_u32 s100, 0
	s_cbranch_scc1 .Lqp_w1
	s_waitcnt vmcnt(1)

.Lqp_rows:
	v_readfirstlane_b32 s100, v244
	s_nop 3
	s_lshr_b32 s100, s100, 6
	s_lshl_b32 s100, s100, 5
	s_add_u32 s98, s98, s100
	s_addc_u32 s99, s99, 0
	s_lshl_b64 s[98:99], s[98:99], 11
	s_add_u32 s98, s98, s94
	s_addc_u32 s99, s99, s95
	s_lshl_b32 s101, s101, 1
	s_add_u32 s98, s98, s101
	s_addc_u32 s99, s99, 0
	v_and_b32_e32 v226, 31, v244
	v_lshlrev_b32_e32 v226, 11, v226
	v_bfe_u32 v227, v244, 5, 1
	v_lshl_or_b32 v226, v227, 4, v226
	global_load_dwordx4 v[188:191], v226, s[98:99]
	global_load_dwordx4 v[192:195], v226, s[98:99] offset:32
	global_load_dwordx4 v[196:199], v226, s[98:99] offset:64
	global_load_dwordx4 v[200:203], v226, s[98:99] offset:96
	s_mov_b32 s100, 1
	s_cmp_lg_u64 s[72:73], 0
	s_cbranch_scc0 .Lkp_done
	s_mov_b32 s100, 2

.LBB0_321:
	v_add_f32_e32 v2, v96, v97
	v_add_f32_e32 v2, v98, v2
	v_add_f32_e32 v2, v99, v2
	v_add_f32_e32 v2, v100, v2
	v_add_f32_e32 v2, v101, v2
	v_add_f32_e32 v2, v102, v2
	v_add_f32_e32 v2, v103, v2
	v_add_f32_e32 v2, v104, v2
	v_add_f32_e32 v2, v105, v2
	v_add_f32_e32 v2, v106, v2
	v_add_f32_e32 v2, v107, v2
	v_add_f32_e32 v2, v108, v2
	v_add_f32_e32 v2, v109, v2
	v_add_f32_e32 v2, v110, v2
	v_add_f32_e32 v2, v111, v2
	v_add_f32_e32 v2, v2, v80
	v_add_f32_e32 v2, v81, v2
	v_add_f32_e32 v2, v82, v2
	v_add_f32_e32 v2, v83, v2
	v_add_f32_e32 v2, v84, v2
	v_add_f32_e32 v2, v85, v2
	v_add_f32_e32 v2, v86, v2
	v_add_f32_e32 v2, v87, v2
	v_add_f32_e32 v2, v88, v2
	v_add_f32_e32 v2, v89, v2
	v_add_f32_e32 v2, v90, v2
	v_add_f32_e32 v2, v91, v2
	v_add_f32_e32 v2, v92, v2
	s_cmp_lg_u32 0, -1
	v_add_f32_e32 v2, v93, v2
	s_cselect_b32 s0, 0, 0
	v_add_f32_e32 v2, v94, v2
	s_addk_i32 s0, 0x6000
	v_add_f32_e32 v2, v95, v2
	v_add3_u32 v3, v241, s0, v238
	v_add_f32_e32 v2, v14, v2
	v_cvt_pk_bf16_f32 v4, v96, v97
	v_cvt_pk_bf16_f32 v5, v98, v99
	v_cvt_pk_bf16_f32 v6, v100, v101
	v_cvt_pk_bf16_f32 v7, v102, v103
	v_cvt_pk_bf16_f32 v8, v104, v105
	v_cvt_pk_bf16_f32 v9, v106, v107
	v_cvt_pk_bf16_f32 v10, v108, v109
	v_cvt_pk_bf16_f32 v11, v110, v111
	v_cvt_pk_bf16_f32 v12, v80, v81
	v_cvt_pk_bf16_f32 v13, v82, v83
	v_cvt_pk_bf16_f32 v14, v84, v85
	v_cvt_pk_bf16_f32 v15, v86, v87
	v_cvt_pk_bf16_f32 v80, v88, v89
	v_cvt_pk_bf16_f32 v81, v90, v91
	v_cvt_pk_bf16_f32 v82, v92, v93
	v_cvt_pk_bf16_f32 v83, v94, v95
	s_lshl_b32 s0, s50, 1
	v_add3_u32 v3, v3, v239, s0
	ds_read_b64_tr_b16 v[84:85],v3 offset:0
	ds_read_b64_tr_b16 v[86:87],v3 offset:512
	ds_read_b64_tr_b16 v[88:89],v3 offset:1024
	ds_read_b64_tr_b16 v[90:91],v3 offset:1536
	ds_read_b64_tr_b16 v[92:93],v3 offset:2048
	ds_read_b64_tr_b16 v[94:95],v3 offset:2560
	ds_read_b64_tr_b16 v[96:97],v3 offset:3072
	ds_read_b64_tr_b16 v[98:99],v3 offset:3584
	s_waitcnt lgkmcnt(0)
	s_nop 0
	v_mfma_f32_32x32x16_bf16 v[16:31], v[4:7], v[84:87], v[16:31]
	ds_read_b64_tr_b16 v[84:85],v3 offset:4096
	ds_read_b64_tr_b16 v[86:87],v3 offset:4608
	v_mfma_f32_32x32x16_bf16 v[16:31], v[8:11], v[88:91], v[16:31]
	ds_read_b64_tr_b16 v[88:89],v3 offset:5120
	ds_read_b64_tr_b16 v[90:91],v3 offset:5632
	v_mfma_f32_32x32x16_bf16 v[16:31], v[12:15], v[92:95], v[16:31]
	ds_read_b64_tr_b16 v[92:93],v3 offset:6144
	ds_read_b64_tr_b16 v[94:95],v3 offset:6656
	v_mfma_f32_32x32x16_bf16 v[16:31], v[80:83], v[96:99], v[16:31]
	ds_read_b64_tr_b16 v[96:97],v3 offset:7168
	ds_read_b64_tr_b16 v[98:99],v3 offset:7680
	s_waitcnt lgkmcnt(0)
	v_mfma_f32_32x32x16_bf16 v[32:47], v[4:7], v[84:87], v[32:47]
	v_add_u32_e32 v3, 0x2000, v3
	ds_read_b64_tr_b16 v[84:85],v3 offset:0
	ds_read_b64_tr_b16 v[86:87],v3 offset:512
	v_mfma_f32_32x32x16_bf16 v[32:47], v[8:11], v[88:91], v[32:47]
	ds_read_b64_tr_b16 v[88:89],v3 offset:1024
	ds_read_b64_tr_b16 v[90:91],v3 offset:1536
	v_mfma_f32_32x32x16_bf16 v[32:47], v[12:15], v[92:95], v[32:47]
	ds_read_b64_tr_b16 v[92:93],v3 offset:2048
	ds_read_b64_tr_b16 v[94:95],v3 offset:2560
	v_mfma_f32_32x32x16_bf16 v[32:47], v[80:83], v[96:99], v[32:47]
	ds_read_b64_tr_b16 v[96:97],v3 offset:3072
	ds_read_b64_tr_b16 v[98:99],v3 offset:3584
	s_waitcnt lgkmcnt(0)
	v_mfma_f32_32x32x16_bf16 v[48:63], v[4:7], v[84:87], v[48:63]
	ds_read_b64_tr_b16 v[84:85],v3 offset:4096
	ds_read_b64_tr_b16 v[86:87],v3 offset:4608
	v_mfma_f32_32x32x16_bf16 v[48:63], v[8:11], v[88:91], v[48:63]
	ds_read_b64_tr_b16 v[88:89],v3 offset:5120
	ds_read_b64_tr_b16 v[90:91],v3 offset:5632
	v_mfma_f32_32x32x16_bf16 v[48:63], v[12:15], v[92:95], v[48:63]
	ds_read_b64_tr_b16 v[92:93],v3 offset:6144
	ds_read_b64_tr_b16 v[94:95],v3 offset:6656
	v_mfma_f32_32x32x16_bf16 v[48:63], v[80:83], v[96:99], v[48:63]
	ds_read_b64_tr_b16 v[96:97],v3 offset:7168
	ds_read_b64_tr_b16 v[98:99],v3 offset:7680
	s_waitcnt lgkmcnt(0)
	v_mfma_f32_32x32x16_bf16 v[64:79], v[4:7], v[84:87], v[64:79]
	v_mov_b32_e32 v3, v2
	s_nop 1
	v_permlane32_swap_b32_e32 v2, v3
	v_cmp_gt_u32_e32 vcc, 32, v235
	v_mfma_f32_32x32x16_bf16 v[64:79], v[8:11], v[88:91], v[64:79]
	v_mfma_f32_32x32x16_bf16 v[64:79], v[12:15], v[92:95], v[64:79]
	v_mfma_f32_32x32x16_bf16 v[64:79], v[80:83], v[96:99], v[64:79]
	s_cmp_lg_u32 s100, 0
	s_cbranch_scc0 .Lvp_done
	s_barrier
	v_lshrrev_b32_e32 v227, 6, v244
	v_and_b32_e32 v228, 3, v227
	v_lshlrev_b32_e32 v228, 4, v228
	v_bfe_u32 v229, v244, 2, 4
	v_or_b32_e32 v228, v228, v229
	v_lshlrev_b32_e32 v228, 11, v228
	v_lshrrev_b32_e32 v227, 2, v227
	v_lshl_add_u32 v228, v227, 6, v228
	v_and_b32_e32 v229, 3, v244
	v_lshl_add_u32 v228, v229, 4, v228
	s_mov_b32 s101, m0
	s_add_i32 m0, s46, 0x6000
	s_nop 0
	global_load_lds_dwordx4 v228, s[62:63]
	s_add_i32 m0, s46, 0x7f80
	s_nop 0
	global_load_lds_dwordx4 v228, s[62:63] offset:128
	s_mov_b32 m0, s101
.Lvp_done:
	s_and_saveexec_b64 s[0:1], vcc
	v_add_f32_e32 v2, v2, v3
	ds_write_b32 v240, v2 offset:128
	s_or_b64 exec, exec, s[0:1]
	s_waitcnt lgkmcnt(0)
	ds_read_b128 v[2:5], v0 offset:128
	ds_read_b128 v[6:9], v0 offset:160
	s_lshl_b32 s0, s44, 13
	s_add_i32 s2, s0, 0
	s_add_i32 s2, s2, 0x12800
	s_waitcnt lgkmcnt(1)
	v_rcp_f32_e32 v10, v2
	v_rcp_f32_e32 v11, v3
	v_rcp_f32_e32 v12, v4
	v_rcp_f32_e32 v13, v5
	s_waitcnt lgkmcnt(0)
	v_rcp_f32_e32 v14, v6
	ds_read_b128 v[2:5], v0 offset:192
	v_rcp_f32_e32 v15, v7
	v_rcp_f32_e32 v81, v8
	v_rcp_f32_e32 v82, v9
	ds_read_b128 v[6:9], v0 offset:224
	s_waitcnt lgkmcnt(1)
	v_rcp_f32_e32 v0, v2
	v_rcp_f32_e32 v2, v3
	v_rcp_f32_e32 v3, v4
	v_rcp_f32_e32 v4, v5
	s_waitcnt lgkmcnt(0)
	v_rcp_f32_e32 v5, v6
	v_rcp_f32_e32 v6, v7
	v_rcp_f32_e32 v7, v8
	v_rcp_f32_e32 v8, v9
	v_lshlrev_b32_e32 v131, 8, v237
	s_mov_b64 s[0:1], -1
	s_andn2_b64 vcc, exec, s[72:73]
	v_lshl_add_u32 v80, v236, 1, s2
	v_mul_f32_e32 v133, v16, v10
	v_mul_f32_e32 v132, v32, v10
	v_mul_f32_e32 v130, v48, v10
	v_mul_f32_e32 v129, v64, v10
	v_mul_f32_e32 v128, v17, v11
	v_mul_f32_e32 v127, v33, v11
	v_mul_f32_e32 v126, v49, v11
	v_mul_f32_e32 v125, v65, v11
	v_mul_f32_e32 v124, v18, v12
	v_mul_f32_e32 v123, v34, v12
	v_mul_f32_e32 v122, v50, v12
	v_mul_f32_e32 v121, v66, v12
	v_mul_f32_e32 v120, v19, v13
	v_mul_f32_e32 v119, v35, v13
	v_mul_f32_e32 v118, v51, v13
	v_mul_f32_e32 v117, v67, v13
	v_or_b32_e32 v115, 0x800, v131
	v_mul_f32_e32 v116, v20, v14
	v_mul_f32_e32 v114, v36, v14
	v_mul_f32_e32 v113, v52, v14
	v_mul_f32_e32 v112, v68, v14
	v_or_b32_e32 v110, 0x900, v131
	v_mul_f32_e32 v111, v21, v15
	v_mul_f32_e32 v109, v37, v15
	v_mul_f32_e32 v108, v53, v15
	v_mul_f32_e32 v107, v69, v15
	v_or_b32_e32 v105, 0xa00, v131
	v_mul_f32_e32 v106, v22, v81
	v_mul_f32_e32 v104, v38, v81
	v_mul_f32_e32 v103, v54, v81
	v_mul_f32_e32 v102, v70, v81
	v_or_b32_e32 v100, 0xb00, v131
	v_mul_f32_e32 v101, v23, v82
	v_mul_f32_e32 v99, v39, v82
	v_mul_f32_e32 v98, v55, v82
	v_mul_f32_e32 v97, v71, v82
	v_or_b32_e32 v95, 0x1000, v131
	v_mul_f32_e32 v96, v24, v0
	v_mul_f32_e32 v94, v40, v0
	v_mul_f32_e32 v93, v56, v0
	v_mul_f32_e32 v92, v72, v0
	v_or_b32_e32 v90, 0x1100, v131
	v_mul_f32_e32 v91, v25, v2
	v_mul_f32_e32 v89, v41, v2
	v_mul_f32_e32 v88, v57, v2
	v_mul_f32_e32 v87, v73, v2
	v_or_b32_e32 v85, 0x1200, v131
	v_mul_f32_e32 v86, v26, v3
	v_mul_f32_e32 v84, v42, v3
	v_mul_f32_e32 v83, v58, v3
	v_mul_f32_e32 v82, v74, v3
	v_or_b32_e32 v74, 0x1300, v131
	v_mul_f32_e32 v81, v27, v4
	v_mul_f32_e32 v73, v43, v4
	v_mul_f32_e32 v72, v59, v4
	v_mul_f32_e32 v71, v75, v4
	v_or_b32_e32 v69, 0x1800, v131
	v_mul_f32_e32 v70, v28, v5
	v_mul_f32_e32 v68, v44, v5
	v_mul_f32_e32 v67, v60, v5
	v_mul_f32_e32 v66, v76, v5
	v_or_b32_e32 v64, 0x1900, v131
	v_mul_f32_e32 v65, v29, v6
	v_mul_f32_e32 v60, v45, v6
	v_mul_f32_e32 v59, v61, v6
	v_mul_f32_e32 v58, v77, v6
	v_or_b32_e32 v56, 0x1a00, v131
	v_mul_f32_e32 v57, v30, v7
	v_mul_f32_e32 v55, v46, v7
	v_mul_f32_e32 v54, v62, v7
	v_mul_f32_e32 v53, v78, v7
	v_or_b32_e32 v51, 0x1b00, v131
	v_mul_f32_e32 v52, v31, v8
	v_mul_f32_e32 v50, v47, v8
	v_mul_f32_e32 v49, v63, v8
	v_mul_f32_e32 v48, v79, v8
	s_cbranch_vccnz .LBB0_325
	v_add_u32_e32 v0, v80, v131
	ds_read_u16 v2, v0
	ds_read_u16 v3, v0 offset:64
	ds_read_u16 v4, v0 offset:128
	ds_read_u16 v5, v0 offset:192
	ds_read_u16 v6, v0 offset:256
	ds_read_u16 v7, v0 offset:320
	ds_read_u16 v8, v0 offset:384
	ds_read_u16 v9, v0 offset:448
	s_waitcnt lgkmcnt(7)
	v_lshlrev_b32_e32 v2, 16, v2
	v_fma_f32 v2, -v233, v133, v2
	v_cvt_pk_bf16_f32 v2, v2, s0
	ds_write_b16 v0, v2
	s_waitcnt lgkmcnt(7)
	v_lshlrev_b32_e32 v2, 16, v3
	v_fma_f32 v2, -v233, v132, v2
	v_cvt_pk_bf16_f32 v2, v2, s0
	ds_write_b16 v0, v2 offset:64
	s_waitcnt lgkmcnt(7)
	v_lshlrev_b32_e32 v2, 16, v4
	v_fma_f32 v2, -v233, v130, v2
	v_cvt_pk_bf16_f32 v2, v2, s0
	ds_write_b16 v0, v2 offset:128
	s_waitcnt lgkmcnt(7)
	v_lshlrev_b32_e32 v2, 16, v5
	v_fma_f32 v2, -v233, v129, v2
	v_cvt_pk_bf16_f32 v2, v2, s0
	ds_write_b16 v0, v2 offset:192
	s_waitcnt lgkmcnt(7)
	v_lshlrev_b32_e32 v2, 16, v6
	v_fma_f32 v2, -v233, v128, v2
	v_cvt_pk_bf16_f32 v2, v2, s0
	ds_write_b16 v0, v2 offset:256
	s_waitcnt lgkmcnt(7)
	v_lshlrev_b32_e32 v2, 16, v7
	v_fma_f32 v2, -v233, v127, v2
	v_cvt_pk_bf16_f32 v2, v2, s0
	ds_write_b16 v0, v2 offset:320
	s_waitcnt lgkmcnt(7)
	v_lshlrev_b32_e32 v2, 16, v8
	v_fma_f32 v2, -v233, v126, v2
	v_cvt_pk_bf16_f32 v2, v2, s0
	ds_write_b16 v0, v2 offset:384
	s_waitcnt lgkmcnt(7)
	v_lshlrev_b32_e32 v2, 16, v9
	v_fma_f32 v2, -v233, v125, v2
	v_cvt_pk_bf16_f32 v2, v2, s0
	ds_write_b16 v0, v2 offset:448
	ds_read_u16 v2, v0 offset:512
	ds_read_u16 v3, v0 offset:576
	ds_read_u16 v4, v0 offset:640
	ds_read_u16 v5, v0 offset:704
	ds_read_u16 v6, v0 offset:768
	ds_read_u16 v7, v0 offset:832
	ds_read_u16 v8, v0 offset:896
	ds_read_u16 v9, v0 offset:960
	s_waitcnt lgkmcnt(7)
	v_lshlrev_b32_e32 v2, 16, v2
	v_fma_f32 v2, -v233, v124, v2
	v_cvt_pk_bf16_f32 v2, v2, s0
	ds_write_b16 v0, v2 offset:512
	s_waitcnt lgkmcnt(7)
	v_lshlrev_b32_e32 v2, 16, v3
	v_fma_f32 v2, -v233, v123, v2
	v_cvt_pk_bf16_f32 v2, v2, s0
	ds_write_b16 v0, v2 offset:576
	s_waitcnt lgkmcnt(7)
	v_lshlrev_b32_e32 v2, 16, v4
	v_fma_f32 v2, -v233, v122, v2
	v_cvt_pk_bf16_f32 v2, v2, s0
	ds_write_b16 v0, v2 offset:640
	s_waitcnt lgkmcnt(7)
	v_lshlrev_b32_e32 v2, 16, v5
	v_fma_f32 v2, -v233, v121, v2
	v_cvt_pk_bf16_f32 v2, v2, s0
	ds_write_b16 v0, v2 offset:704
	s_waitcnt lgkmcnt(7)
	v_lshlrev_b32_e32 v2, 16, v6
	v_fma_f32 v2, -v233, v120, v2
	v_cvt_pk_bf16_f32 v2, v2, s0
	ds_write_b16 v0, v2 offset:768
	s_waitcnt lgkmcnt(7)
	v_lshlrev_b32_e32 v2, 16, v7
	v_fma_f32 v2, -v233, v119, v2
	v_cvt_pk_bf16_f32 v2, v2, s0
	ds_write_b16 v0, v2 offset:832
	s_waitcnt lgkmcnt(7)
	v_lshlrev_b32_e32 v2, 16, v8
	v_fma_f32 v2, -v233, v118, v2
	v_cvt_pk_bf16_f32 v2, v2, s0
	ds_write_b16 v0, v2 offset:896
	s_waitcnt lgkmcnt(7)
	v_lshlrev_b32_e32 v2, 16, v9
	v_fma_f32 v2, -v233, v117, v2
	v_cvt_pk_bf16_f32 v2, v2, s0
	ds_write_b16 v0, v2 offset:960
	v_add_u32_e32 v0, v80, v115
	ds_read_u16 v2, v0
	ds_read_u16 v3, v0 offset:64
	ds_read_u16 v4, v0 offset:128
	ds_read_u16 v5, v0 offset:192
	v_lshrrev_b32_e32 v47, 1, v235
	s_waitcnt lgkmcnt(3)
	v_lshlrev_b32_e32 v2, 16, v2
	v_fma_f32 v2, -v233, v116, v2
	v_cvt_pk_bf16_f32 v2, v2, s0
	ds_write_b16 v0, v2
	s_waitcnt lgkmcnt(3)
	v_lshlrev_b32_e32 v2, 16, v3
	v_fma_f32 v2, -v233, v114, v2
	v_cvt_pk_bf16_f32 v2, v2, s0
	ds_write_b16 v0, v2 offset:64
	s_waitcnt lgkmcnt(3)
	v_lshlrev_b32_e32 v2, 16, v4
	v_fma_f32 v2, -v233, v113, v2
	v_cvt_pk_bf16_f32 v2, v2, s0
	ds_write_b16 v0, v2 offset:128
	s_waitcnt lgkmcnt(3)
	v_lshlrev_b32_e32 v2, 16, v5
	v_fma_f32 v2, -v233, v112, v2
	v_cvt_pk_bf16_f32 v2, v2, s0
	ds_write_b16 v0, v2 offset:192
	v_add_u32_e32 v0, v80, v110
	ds_read_u16 v2, v0
	ds_read_u16 v3, v0 offset:64
	ds_read_u16 v4, v0 offset:128
	ds_read_u16 v5, v0 offset:192
	s_waitcnt lgkmcnt(3)
	v_lshlrev_b32_e32 v2, 16, v2
	v_fma_f32 v2, -v233, v111, v2
	v_cvt_pk_bf16_f32 v2, v2, s0
	ds_write_b16 v0, v2
	s_waitcnt lgkmcnt(3)
	v_lshlrev_b32_e32 v2, 16, v3
	v_fma_f32 v2, -v233, v109, v2
	v_cvt_pk_bf16_f32 v2, v2, s0
	ds_write_b16 v0, v2 offset:64
	s_waitcnt lgkmcnt(3)
	v_lshlrev_b32_e32 v2, 16, v4
	v_fma_f32 v2, -v233, v108, v2
	v_cvt_pk_bf16_f32 v2, v2, s0
	ds_write_b16 v0, v2 offset:128
	s_waitcnt lgkmcnt(3)
	v_lshlrev_b32_e32 v2, 16, v5
	v_fma_f32 v2, -v233, v107, v2
	v_cvt_pk_bf16_f32 v2, v2, s0
	ds_write_b16 v0, v2 offset:192
	v_add_u32_e32 v0, v80, v105
	ds_read_u16 v2, v0
	ds_read_u16 v3, v0 offset:64
	ds_read_u16 v4, v0 offset:128
	ds_read_u16 v5, v0 offset:192
	s_waitcnt lgkmcnt(3)
	v_lshlrev_b32_e32 v2, 16, v2
	v_fma_f32 v2, -v233, v106, v2
	v_cvt_pk_bf16_f32 v2, v2, s0
	ds_write_b16 v0, v2
	s_waitcnt lgkmcnt(3)
	v_lshlrev_b32_e32 v2, 16, v3
	v_fma_f32 v2, -v233, v104, v2
	v_cvt_pk_bf16_f32 v2, v2, s0
	ds_write_b16 v0, v2 offset:64
	s_waitcnt lgkmcnt(3)
	v_lshlrev_b32_e32 v2, 16, v4
	v_fma_f32 v2, -v233, v103, v2
	v_cvt_pk_bf16_f32 v2, v2, s0
	ds_write_b16 v0, v2 offset:128
	s_waitcnt lgkmcnt(3)
	v_lshlrev_b32_e32 v2, 16, v5
	v_fma_f32 v2, -v233, v102, v2
	v_cvt_pk_bf16_f32 v2, v2, s0
	ds_write_b16 v0, v2 offset:192
	v_add_u32_e32 v0, v80, v100
	ds_read_u16 v2, v0
	ds_read_u16 v3, v0 offset:64
	ds_read_u16 v4, v0 offset:128
	ds_read_u16 v5, v0 offset:192
	s_waitcnt lgkmcnt(3)
	v_lshlrev_b32_e32 v2, 16, v2
	v_fma_f32 v2, -v233, v101, v2
	v_cvt_pk_bf16_f32 v2, v2, s0
	ds_write_b16 v0, v2
	s_waitcnt lgkmcnt(3)
	v_lshlrev_b32_e32 v2, 16, v3
	v_fma_f32 v2, -v233, v99, v2
	v_cvt_pk_bf16_f32 v2, v2, s0
	ds_write_b16 v0, v2 offset:64
	s_waitcnt lgkmcnt(3)
	v_lshlrev_b32_e32 v2, 16, v4
	v_fma_f32 v2, -v233, v98, v2
	v_cvt_pk_bf16_f32 v2, v2, s0
	ds_write_b16 v0, v2 offset:128
	s_waitcnt lgkmcnt(3)
	v_lshlrev_b32_e32 v2, 16, v5
	v_fma_f32 v2, -v233, v97, v2
	v_cvt_pk_bf16_f32 v2, v2, s0
	ds_write_b16 v0, v2 offset:192
	v_add_u32_e32 v0, v80, v95
	ds_read_u16 v2, v0
	ds_read_u16 v3, v0 offset:64
	ds_read_u16 v4, v0 offset:128
	ds_read_u16 v5, v0 offset:192
	s_waitcnt lgkmcnt(3)
	v_lshlrev_b32_e32 v2, 16, v2
	v_fma_f32 v2, -v233, v96, v2
	v_cvt_pk_bf16_f32 v2, v2, s0
	ds_write_b16 v0, v2
	s_waitcnt lgkmcnt(3)
	v_lshlrev_b32_e32 v2, 16, v3
	v_fma_f32 v2, -v233, v94, v2
	v_cvt_pk_bf16_f32 v2, v2, s0
	ds_write_b16 v0, v2 offset:64
	s_waitcnt lgkmcnt(3)
	v_lshlrev_b32_e32 v2, 16, v4
	v_fma_f32 v2, -v233, v93, v2
	v_cvt_pk_bf16_f32 v2, v2, s0
	ds_write_b16 v0, v2 offset:128
	s_waitcnt lgkmcnt(3)
	v_lshlrev_b32_e32 v2, 16, v5
	v_fma_f32 v2, -v233, v92, v2
	v_cvt_pk_bf16_f32 v2, v2, s0
	ds_write_b16 v0, v2 offset:192
	v_add_u32_e32 v0, v80, v90
	ds_read_u16 v2, v0
	ds_read_u16 v3, v0 offset:64
	ds_read_u16 v4, v0 offset:128
	ds_read_u16 v5, v0 offset:192
	s_waitcnt lgkmcnt(3)
	v_lshlrev_b32_e32 v2, 16, v2
	v_fma_f32 v2, -v233, v91, v2
	v_cvt_pk_bf16_f32 v2, v2, s0
	ds_write_b16 v0, v2
	s_waitcnt lgkmcnt(3)
	v_lshlrev_b32_e32 v2, 16, v3
	v_fma_f32 v2, -v233, v89, v2
	v_cvt_pk_bf16_f32 v2, v2, s0
	ds_write_b16 v0, v2 offset:64
	s_waitcnt lgkmcnt(3)
	v_lshlrev_b32_e32 v2, 16, v4
	v_fma_f32 v2, -v233, v88, v2
	v_cvt_pk_bf16_f32 v2, v2, s0
	ds_write_b16 v0, v2 offset:128
	s_waitcnt lgkmcnt(3)
	v_lshlrev_b32_e32 v2, 16, v5
	v_fma_f32 v2, -v233, v87, v2
	v_cvt_pk_bf16_f32 v2, v2, s0
	ds_write_b16 v0, v2 offset:192
	v_add_u32_e32 v0, v80, v85
	ds_read_u16 v2, v0
	ds_read_u16 v3, v0 offset:64
	ds_read_u16 v4, v0 offset:128
	ds_read_u16 v5, v0 offset:192
	s_waitcnt lgkmcnt(3)
	v_lshlrev_b32_e32 v2, 16, v2
	v_fma_f32 v2, -v233, v86, v2
	v_cvt_pk_bf16_f32 v2, v2, s0
	ds_write_b16 v0, v2
	s_waitcnt lgkmcnt(3)
	v_lshlrev_b32_e32 v2, 16, v3
	v_fma_f32 v2, -v233, v84, v2
	v_cvt_pk_bf16_f32 v2, v2, s0
	ds_write_b16 v0, v2 offset:64
	s_waitcnt lgkmcnt(3)
	v_lshlrev_b32_e32 v2, 16, v4
	v_fma_f32 v2, -v233, v83, v2
	v_cvt_pk_bf16_f32 v2, v2, s0
	ds_write_b16 v0, v2 offset:128
	s_waitcnt lgkmcnt(3)
	v_lshlrev_b32_e32 v2, 16, v5
	v_fma_f32 v2, -v233, v82, v2
	v_cvt_pk_bf16_f32 v2, v2, s0
	ds_write_b16 v0, v2 offset:192
	v_add_u32_e32 v0, v80, v74
	ds_read_u16 v2, v0
	ds_read_u16 v3, v0 offset:64
	ds_read_u16 v4, v0 offset:128
	ds_read_u16 v5, v0 offset:192
	s_waitcnt lgkmcnt(3)
	v_lshlrev_b32_e32 v2, 16, v2
	v_fma_f32 v2, -v233, v81, v2
	v_cvt_pk_bf16_f32 v2, v2, s0
	ds_write_b16 v0, v2
	s_waitcnt lgkmcnt(3)
	v_lshlrev_b32_e32 v2, 16, v3
	v_fma_f32 v2, -v233, v73, v2
	v_cvt_pk_bf16_f32 v2, v2, s0
	ds_write_b16 v0, v2 offset:64
	s_waitcnt lgkmcnt(3)
	v_lshlrev_b32_e32 v2, 16, v4
	v_fma_f32 v2, -v233, v72, v2
	v_cvt_pk_bf16_f32 v2, v2, s0
	ds_write_b16 v0, v2 offset:128
	s_waitcnt lgkmcnt(3)
	v_lshlrev_b32_e32 v2, 16, v5
	v_fma_f32 v2, -v233, v71, v2
	v_cvt_pk_bf16_f32 v2, v2, s0
	ds_write_b16 v0, v2 offset:192
	v_add_u32_e32 v0, v80, v69
	ds_read_u16 v2, v0
	ds_read_u16 v3, v0 offset:64
	ds_read_u16 v4, v0 offset:128
	ds_read_u16 v5, v0 offset:192
	s_waitcnt lgkmcnt(3)
	v_lshlrev_b32_e32 v2, 16, v2
	v_fma_f32 v2, -v233, v70, v2
	v_cvt_pk_bf16_f32 v2, v2, s0
	ds_write_b16 v0, v2
	s_waitcnt lgkmcnt(3)
	v_lshlrev_b32_e32 v2, 16, v3
	v_fma_f32 v2, -v233, v68, v2
	v_cvt_pk_bf16_f32 v2, v2, s0
	ds_write_b16 v0, v2 offset:64
	s_waitcnt lgkmcnt(3)
	v_lshlrev_b32_e32 v2, 16, v4
	v_fma_f32 v2, -v233, v67, v2
	v_cvt_pk_bf16_f32 v2, v2, s0
	ds_write_b16 v0, v2 offset:128
	s_waitcnt lgkmcnt(3)
	v_lshlrev_b32_e32 v2, 16, v5
	v_fma_f32 v2, -v233, v66, v2
	v_cvt_pk_bf16_f32 v2, v2, s0
	ds_write_b16 v0, v2 offset:192
	v_add_u32_e32 v0, v80, v64
	ds_read_u16 v2, v0
	ds_read_u16 v3, v0 offset:64
	ds_read_u16 v4, v0 offset:128
	ds_read_u16 v5, v0 offset:192
	s_waitcnt lgkmcnt(3)
	v_lshlrev_b32_e32 v2, 16, v2
	v_fma_f32 v2, -v233, v65, v2
	v_cvt_pk_bf16_f32 v2, v2, s0
	ds_write_b16 v0, v2
	s_waitcnt lgkmcnt(3)
	v_lshlrev_b32_e32 v2, 16, v3
	v_fma_f32 v2, -v233, v60, v2
	v_cvt_pk_bf16_f32 v2, v2, s0
	ds_write_b16 v0, v2 offset:64
	s_waitcnt lgkmcnt(3)
	v_lshlrev_b32_e32 v2, 16, v4
	v_fma_f32 v2, -v233, v59, v2
	v_cvt_pk_bf16_f32 v2, v2, s0
	ds_write_b16 v0, v2 offset:128
	s_waitcnt lgkmcnt(3)
	v_lshlrev_b32_e32 v2, 16, v5
	v_fma_f32 v2, -v233, v58, v2
	v_cvt_pk_bf16_f32 v2, v2, s0
	ds_write_b16 v0, v2 offset:192
	v_add_u32_e32 v0, v80, v56
	ds_read_u16 v2, v0
	ds_read_u16 v3, v0 offset:64
	ds_read_u16 v4, v0 offset:128
	ds_read_u16 v5, v0 offset:192
	s_waitcnt lgkmcnt(3)
	v_lshlrev_b32_e32 v2, 16, v2
	v_fma_f32 v2, -v233, v57, v2
	v_cvt_pk_bf16_f32 v2, v2, s0
	ds_write_b16 v0, v2
	s_waitcnt lgkmcnt(3)
	v_lshlrev_b32_e32 v2, 16, v3
	v_fma_f32 v2, -v233, v55, v2
	v_cvt_pk_bf16_f32 v2, v2, s0
	ds_write_b16 v0, v2 offset:64
	s_waitcnt lgkmcnt(3)
	v_lshlrev_b32_e32 v2, 16, v4
	v_fma_f32 v2, -v233, v54, v2
	v_cvt_pk_bf16_f32 v2, v2, s0
	ds_write_b16 v0, v2 offset:128
	s_waitcnt lgkmcnt(3)
	v_lshlrev_b32_e32 v2, 16, v5
	v_fma_f32 v2, -v233, v53, v2
	v_cvt_pk_bf16_f32 v2, v2, s0
	ds_write_b16 v0, v2 offset:192
	v_add_u32_e32 v0, v80, v51
	ds_read_u16 v2, v0
	ds_read_u16 v3, v0 offset:64
	ds_read_u16 v4, v0 offset:128
	ds_read_u16 v5, v0 offset:192
	s_waitcnt lgkmcnt(3)
	v_lshlrev_b32_e32 v2, 16, v2
	v_fma_f32 v2, -v233, v52, v2
	v_cvt_pk_bf16_f32 v2, v2, s0
	ds_write_b16 v0, v2
	s_waitcnt lgkmcnt(3)
	v_lshlrev_b32_e32 v2, 16, v3
	v_fma_f32 v2, -v233, v50, v2
	v_cvt_pk_bf16_f32 v2, v2, s0
	ds_write_b16 v0, v2 offset:64
	s_waitcnt lgkmcnt(3)
	v_lshlrev_b32_e32 v2, 16, v4
	v_fma_f32 v2, -v233, v49, v2
	v_cvt_pk_bf16_f32 v2, v2, s0
	ds_write_b16 v0, v2 offset:128
	s_waitcnt lgkmcnt(3)
	v_lshlrev_b32_e32 v2, 16, v5
	v_fma_f32 v2, -v233, v48, v2
	v_cvt_pk_bf16_f32 v2, v2, s0
	ds_write_b16 v0, v2 offset:192
	v_lshlrev_b32_e32 v2, 6, v234
	v_and_b32_e32 v61, 64, v2
	v_lshlrev_b32_e32 v0, 8, v47
	v_lshlrev_b32_e32 v46, 1, v61
	s_waitcnt lgkmcnt(0)
	v_add3_u32 v75, s2, v0, v46
	ds_read_b128 v[6:9], v75 offset:16
	ds_read_b128 v[38:41], v75
	ds_read_b128 v[42:45], v75 offset:32
	ds_read_b128 v[2:5], v75 offset:48
	ds_read_b128 v[76:79], v75 offset:80
	s_waitcnt lgkmcnt(4)
	v_and_b32_e32 v31, 0xffff0000, v7
	v_and_b32_e32 v30, 0xffff0000, v6
	v_lshlrev_b32_e32 v35, 16, v7
	v_lshlrev_b32_e32 v34, 16, v6
	v_pk_mul_f32 v[6:7], v[30:31], v[30:31]
	v_and_b32_e32 v33, 0xffff0000, v9
	v_and_b32_e32 v32, 0xffff0000, v8
	v_pk_fma_f32 v[6:7], v[34:35], v[34:35], v[6:7]
	v_lshlrev_b32_e32 v37, 16, v9
	v_lshlrev_b32_e32 v36, 16, v8
	v_pk_mul_f32 v[8:9], v[32:33], v[32:33]
	v_pk_add_f32 v[6:7], v[6:7], v[6:7] op_sel:[0,1] op_sel_hi:[1,0]
	v_pk_fma_f32 v[8:9], v[36:37], v[36:37], v[8:9]
	s_waitcnt lgkmcnt(0)
	v_lshlrev_b32_e32 v13, 16, v77
	v_pk_add_f32 v[6:7], v[8:9], v[6:7]
	v_lshlrev_b32_e32 v12, 16, v76
	v_pk_add_f32 v[62:63], v[8:9], v[6:7] op_sel:[1,0] op_sel_hi:[0,1]
	ds_read_b128 v[6:9], v75 offset:64
	v_lshlrev_b32_e32 v61, 2, v61
	v_lshlrev_b32_e32 v21, 16, v79
	v_lshlrev_b32_e32 v20, 16, v78
	ds_read_b128 v[134:137], v75 offset:112
	s_waitcnt lgkmcnt(1)
	v_and_b32_e32 v17, 0xffff0000, v7
	v_and_b32_e32 v16, 0xffff0000, v6
	v_lshlrev_b32_e32 v23, 16, v7
	v_lshlrev_b32_e32 v22, 16, v6
	v_pk_mul_f32 v[6:7], v[16:17], v[16:17]
	v_and_b32_e32 v19, 0xffff0000, v9
	v_and_b32_e32 v18, 0xffff0000, v8
	v_pk_fma_f32 v[6:7], v[22:23], v[22:23], v[6:7]
	v_lshlrev_b32_e32 v25, 16, v9
	v_lshlrev_b32_e32 v24, 16, v8
	v_pk_mul_f32 v[8:9], v[18:19], v[18:19]
	v_pk_add_f32 v[6:7], v[6:7], v[6:7] op_sel:[0,1] op_sel_hi:[1,0]
	v_pk_fma_f32 v[8:9], v[24:25], v[24:25], v[8:9]
	v_and_b32_e32 v27, 0xffff0000, v42
	v_pk_add_f32 v[6:7], v[8:9], v[6:7]
	v_lshlrev_b32_e32 v26, 16, v42
	v_pk_add_f32 v[150:151], v[8:9], v[6:7] op_sel:[1,0] op_sel_hi:[0,1]
	v_and_b32_e32 v7, 0xffff0000, v77
	v_and_b32_e32 v6, 0xffff0000, v76
	v_pk_mul_f32 v[8:9], v[6:7], v[6:7]
	v_mul_f32_e32 v0, v27, v27
	v_pk_fma_f32 v[8:9], v[12:13], v[12:13], v[8:9]
	v_and_b32_e32 v29, 0xffff0000, v43
	v_pk_add_f32 v[10:11], v[8:9], v[8:9] op_sel:[0,1] op_sel_hi:[1,0]
	v_and_b32_e32 v9, 0xffff0000, v79
	v_and_b32_e32 v8, 0xffff0000, v78
	ds_read_b128 v[76:79], v75 offset:96
	s_lshl_b32 s98, s44, 9
	s_add_i32 s98, s98, 0x23000
	v_add_u32_e32 v204, s98, v61
	ds_read_b128 v[138:141], v204 offset:16
	ds_read_b128 v[142:145], v204
	v_pk_mul_f32 v[14:15], v[8:9], v[8:9]
	v_pk_fma_f32 v[146:147], v[26:27], v[26:27], v[0:1] op_sel_hi:[1,1,0]
	v_pk_fma_f32 v[14:15], v[20:21], v[20:21], v[14:15]
	v_lshlrev_b32_e32 v28, 16, v43
	v_pk_add_f32 v[10:11], v[14:15], v[10:11]
	v_mul_f32_e32 v0, v29, v29
	v_pk_add_f32 v[152:153], v[14:15], v[10:11] op_sel:[1,0] op_sel_hi:[0,1]
	s_waitcnt lgkmcnt(0)
	v_and_b32_e32 v11, 0xffff0000, v76
	v_pk_fma_f32 v[148:149], v[28:29], v[28:29], v[0:1] op_sel_hi:[1,1,0]
	v_lshlrev_b32_e32 v10, 16, v76
	v_mul_f32_e32 v0, v11, v11
	v_and_b32_e32 v15, 0xffff0000, v77
	v_pk_fma_f32 v[154:155], v[10:11], v[10:11], v[0:1] op_sel_hi:[1,1,0]
	v_lshlrev_b32_e32 v14, 16, v77
	v_mul_f32_e32 v0, v15, v15
	v_and_b32_e32 v157, 0xffff0000, v41
	v_and_b32_e32 v161, 0xffff0000, v40
	v_and_b32_e32 v165, 0xffff0000, v38
	v_pk_fma_f32 v[76:77], v[14:15], v[14:15], v[0:1] op_sel_hi:[1,1,0]
	v_lshlrev_b32_e32 v156, 16, v41
	v_mul_f32_e32 v0, v157, v157
	v_lshlrev_b32_e32 v160, 16, v40
	v_and_b32_e32 v163, 0xffff0000, v39
	v_lshlrev_b32_e32 v164, 16, v38
	v_mov_b32_e32 v42, v161
	v_mov_b32_e32 v43, v165
	v_pk_fma_f32 v[158:159], v[156:157], v[156:157], v[0:1] op_sel_hi:[1,1,0]
	v_lshlrev_b32_e32 v162, 16, v39
	v_mul_f32_e32 v0, v163, v163
	v_mov_b32_e32 v38, v160
	v_mov_b32_e32 v39, v164
	v_pk_mul_f32 v[42:43], v[42:43], v[42:43]
	v_pk_fma_f32 v[40:41], v[162:163], v[162:163], v[0:1] op_sel_hi:[1,1,0]
	v_pk_fma_f32 v[38:39], v[38:39], v[38:39], v[42:43]
	v_lshlrev_b32_e32 v173, 16, v4
	v_pk_add_f32 v[40:41], v[38:39], v[40:41] op_sel:[1,0] op_sel_hi:[0,1]
	v_pk_add_f32 v[166:167], v[38:39], v[40:41]
	v_pk_mov_b32 v[38:39], v[44:45], v[4:5] op_sel:[1,0]
	v_lshlrev_b32_e32 v182, 16, v5
	v_and_b32_e32 v5, 0xffff0000, v5
	v_and_b32_e32 v4, s0, v4
	v_pk_mul_f32 v[184:185], v[4:5], v[4:5]
	v_pk_add_f32 v[158:159], v[158:159], v[166:167]
	v_mov_b32_e32 v63, v185
	v_mul_f32_e32 v159, v182, v182
	v_pk_add_f32 v[62:63], v[158:159], v[62:63]
	v_lshlrev_b32_e32 v158, 16, v3
	v_and_b32_e32 v159, 0xffff0000, v3
	v_lshlrev_b32_e32 v169, 16, v2
	v_and_b32_e32 v171, 0xffff0000, v2
	v_and_b32_e32 v170, 0xffff0000, v44
	v_pk_mul_f32 v[2:3], v[158:159], v[158:159]
	v_lshlrev_b32_e32 v168, 16, v44
	v_and_b32_e32 v175, 0xffff0000, v39
	v_and_b32_e32 v174, 0xffff0000, v38
	v_pk_mul_f32 v[38:39], v[170:171], v[170:171]
	v_mov_b32_e32 v147, v2
	v_mov_b32_e32 v149, v3
	v_lshlrev_b32_e32 v172, 16, v45
	v_pk_fma_f32 v[176:177], v[168:169], v[168:169], v[38:39]
	v_pk_mul_f32 v[38:39], v[174:175], v[174:175]
	v_pk_add_f32 v[2:3], v[146:147], v[148:149]
	v_pk_fma_f32 v[178:179], v[172:173], v[172:173], v[38:39]
	v_pk_add_f32 v[2:3], v[176:177], v[2:3]
	v_lshlrev_b32_e32 v146, 16, v135
	v_pk_add_f32 v[2:3], v[178:179], v[2:3]
	v_and_b32_e32 v147, 0xffff0000, v135
	v_lshlrev_b32_e32 v41, 16, v134
	v_and_b32_e32 v39, 0xffff0000, v134
	v_and_b32_e32 v38, 0xffff0000, v78
	v_pk_mov_b32 v[42:43], v[78:79], v[136:137] op_sel:[1,0]
	v_pk_add_f32 v[2:3], v[62:63], v[2:3]
	v_pk_mul_f32 v[134:135], v[146:147], v[146:147]
	v_lshlrev_b32_e32 v40, 16, v78
	v_lshlrev_b32_e32 v44, 16, v79
	v_and_b32_e32 v43, 0xffff0000, v43
	v_and_b32_e32 v42, 0xffff0000, v42
	v_pk_mul_f32 v[78:79], v[38:39], v[38:39]
	v_pk_add_f32 v[62:63], v[2:3], v[2:3] op_sel:[0,1] op_sel_hi:[1,0]
	v_mov_b32_e32 v155, v134
	v_mov_b32_e32 v77, v135
	v_lshlrev_b32_e32 v45, 16, v136
	v_pk_fma_f32 v[78:79], v[40:41], v[40:41], v[78:79]
	v_pk_mul_f32 v[180:181], v[42:43], v[42:43]
	v_lshlrev_b32_e32 v2, 16, v137
	v_and_b32_e32 v3, 0xffff0000, v137
	v_pk_add_f32 v[62:63], v[62:63], v[150:151]
	v_pk_add_f32 v[76:77], v[154:155], v[76:77]
	v_pk_fma_f32 v[180:181], v[44:45], v[44:45], v[180:181]
	v_mul_f32_e32 v153, v3, v3
	v_mul_f32_e32 v63, v2, v2
	v_pk_add_f32 v[76:77], v[78:79], v[76:77]
	v_pk_add_f32 v[62:63], v[62:63], v[152:153]
	v_pk_add_f32 v[76:77], v[180:181], v[76:77]
	s_lshl_b64 s[0:1], s[74:75], 1
	v_pk_add_f32 v[62:63], v[62:63], v[76:77]
	s_add_u32 s0, s89, s0
	v_add_f32_e32 v4, v62, v63
	ds_bpermute_b32 v62, v232, v4
	s_addc_u32 s1, s86, s1
	v_lshlrev_b32_e32 v0, 11, v47
	v_mov_b32_e32 v47, v1
	v_mov_b32_e32 v183, v5
	s_waitcnt lgkmcnt(0)
	v_add_f32_e32 v4, v4, v62
	v_fmamk_f32 v4, v4, 0x3c000000, v230
	v_rsq_f32_e32 v4, v4
	v_lshl_add_u64 v[62:63], s[0:1], 0, v[0:1]
	v_lshl_add_u64 v[46:47], v[62:63], 0, v[46:47]
	s_mov_b64 s[0:1], 0
	v_mul_f32_e32 v0, 0x3f4ccccd, v4
	v_pk_mul_f32 v[62:63], v[0:1], v[164:165] op_sel_hi:[0,1]
	s_waitcnt lgkmcnt(0)
	v_pk_mul_f32 v[62:63], v[142:143], v[62:63]
	v_pk_mul_f32 v[26:27], v[0:1], v[26:27] op_sel_hi:[0,1]
	v_cvt_pk_bf16_f32 v76, v62, v63
	v_pk_mul_f32 v[62:63], v[0:1], v[162:163] op_sel_hi:[0,1]
	v_pk_mul_f32 v[62:63], v[144:145], v[62:63]
	v_pk_mul_f32 v[28:29], v[0:1], v[28:29] op_sel_hi:[0,1]
	v_cvt_pk_bf16_f32 v77, v62, v63
	v_pk_mul_f32 v[62:63], v[0:1], v[160:161] op_sel_hi:[0,1]
	v_pk_mul_f32 v[62:63], v[138:139], v[62:63]
	v_mov_b32_e32 v138, v36
	v_cvt_pk_bf16_f32 v78, v62, v63
	v_pk_mul_f32 v[62:63], v[0:1], v[156:157] op_sel_hi:[0,1]
	v_pk_mul_f32 v[62:63], v[140:141], v[62:63]
	v_mov_b32_e32 v139, v32
	v_cvt_pk_bf16_f32 v79, v62, v63
	global_store_dwordx4 v[46:47], v[76:79], off
	ds_read_b128 v[76:79], v204 offset:32
	s_nop 0
	ds_read_b128 v[134:137], v204 offset:48
	v_mov_b32_e32 v62, v34
	v_mov_b32_e32 v63, v30
	v_mov_b32_e32 v30, v35
	v_pk_mul_f32 v[34:35], v[0:1], v[62:63] op_sel_hi:[0,1]
	v_pk_mul_f32 v[30:31], v[0:1], v[30:31] op_sel_hi:[0,1]
	v_mov_b32_e32 v32, v37
	v_mov_b32_e32 v62, v168
	v_mov_b32_e32 v63, v170
	v_mov_b32_e32 v170, v169
	v_pk_mul_f32 v[4:5], v[0:1], v[170:171] op_sel_hi:[0,1]
	v_pk_mul_f32 v[10:11], v[0:1], v[10:11] op_sel_hi:[0,1]
	v_pk_mul_f32 v[14:15], v[0:1], v[14:15] op_sel_hi:[0,1]
	v_pk_mul_f32 v[2:3], v[0:1], v[2:3] op_sel_hi:[0,1]
	s_waitcnt lgkmcnt(1)
	v_pk_mul_f32 v[34:35], v[76:77], v[34:35]
	v_pk_mul_f32 v[30:31], v[78:79], v[30:31]
	v_cvt_pk_bf16_f32 v34, v34, v35
	v_cvt_pk_bf16_f32 v35, v30, v31
	v_pk_mul_f32 v[30:31], v[0:1], v[138:139] op_sel_hi:[0,1]
	s_waitcnt lgkmcnt(0)
	v_pk_mul_f32 v[30:31], v[30:31], v[134:135]
	v_mov_b32_e32 v76, v172
	v_cvt_pk_bf16_f32 v36, v30, v31
	v_pk_mul_f32 v[30:31], v[0:1], v[32:33] op_sel_hi:[0,1]
	v_pk_mul_f32 v[30:31], v[30:31], v[136:137]
	v_mov_b32_e32 v77, v174
	v_cvt_pk_bf16_f32 v37, v30, v31
	global_store_dwordx4 v[46:47], v[34:37], off offset:16
	ds_read_b128 v[30:33], v204 offset:64
	s_nop 0
	ds_read_b128 v[34:37], v204 offset:80
	v_mov_b32_e32 v174, v173
	s_waitcnt lgkmcnt(1)
	v_pk_mul_f32 v[26:27], v[26:27], v[30:31]
	v_pk_mul_f32 v[28:29], v[28:29], v[32:33]
	v_cvt_pk_bf16_f32 v26, v26, v27
	v_cvt_pk_bf16_f32 v27, v28, v29
	v_pk_mul_f32 v[28:29], v[0:1], v[62:63] op_sel_hi:[0,1]
	v_pk_mul_f32 v[30:31], v[0:1], v[76:77] op_sel_hi:[0,1]
	s_waitcnt lgkmcnt(0)
	v_pk_mul_f32 v[28:29], v[28:29], v[34:35]
	v_pk_mul_f32 v[30:31], v[30:31], v[36:37]
	v_cvt_pk_bf16_f32 v28, v28, v29
	v_cvt_pk_bf16_f32 v29, v30, v31
	global_store_dwordx4 v[46:47], v[26:29], off offset:32
	ds_read_b128 v[26:29], v204 offset:96
	s_nop 0
	ds_read_b128 v[30:33], v204 offset:112
	v_mov_b32_e32 v34, v24
	v_mov_b32_e32 v35, v18
	v_mov_b32_e32 v18, v25
	s_waitcnt lgkmcnt(1)
	v_pk_mul_f32 v[4:5], v[4:5], v[26:27]
	s_nop 0
	v_cvt_pk_bf16_f32 v26, v4, v5
	v_pk_mul_f32 v[4:5], v[0:1], v[158:159] op_sel_hi:[0,1]
	v_pk_mul_f32 v[4:5], v[4:5], v[28:29]
	s_nop 0
	v_cvt_pk_bf16_f32 v27, v4, v5
	v_pk_mul_f32 v[4:5], v[0:1], v[174:175] op_sel_hi:[0,1]
	s_waitcnt lgkmcnt(0)
	v_pk_mul_f32 v[4:5], v[4:5], v[30:31]
	s_nop 0
	v_cvt_pk_bf16_f32 v28, v4, v5
	v_pk_mul_f32 v[4:5], v[0:1], v[182:183] op_sel_hi:[0,1]
	v_pk_mul_f32 v[4:5], v[4:5], v[32:33]
	s_nop 0
	v_cvt_pk_bf16_f32 v29, v4, v5
	global_store_dwordx4 v[46:47], v[26:29], off offset:48
	ds_read_b128 v[26:29], v204 offset:128
	s_nop 0
	ds_read_b128 v[30:33], v204 offset:144
	v_mov_b32_e32 v4, v22
	v_mov_b32_e32 v5, v16
	v_pk_mul_f32 v[4:5], v[0:1], v[4:5] op_sel_hi:[0,1]
	v_mov_b32_e32 v16, v23
	s_waitcnt lgkmcnt(1)
	v_pk_mul_f32 v[4:5], v[4:5], v[26:27]
	s_nop 0
	v_cvt_pk_bf16_f32 v22, v4, v5
	v_pk_mul_f32 v[4:5], v[0:1], v[16:17] op_sel_hi:[0,1]
	v_pk_mul_f32 v[4:5], v[4:5], v[28:29]
	s_nop 0
	v_cvt_pk_bf16_f32 v23, v4, v5
	v_pk_mul_f32 v[4:5], v[0:1], v[34:35] op_sel_hi:[0,1]
	s_waitcnt lgkmcnt(0)
	v_pk_mul_f32 v[4:5], v[4:5], v[30:31]
	s_nop 0
	v_cvt_pk_bf16_f32 v24, v4, v5
	v_pk_mul_f32 v[4:5], v[0:1], v[18:19] op_sel_hi:[0,1]
	v_pk_mul_f32 v[4:5], v[4:5], v[32:33]
	s_nop 0
	v_cvt_pk_bf16_f32 v25, v4, v5
	global_store_dwordx4 v[46:47], v[22:25], off offset:64
	ds_read_b128 v[16:19], v204 offset:160
	s_nop 0
	ds_read_b128 v[22:25], v204 offset:176
	v_mov_b32_e32 v4, v12
	v_mov_b32_e32 v5, v6
	v_mov_b32_e32 v6, v13
	v_mov_b32_e32 v12, v20
	v_mov_b32_e32 v13, v8
	v_mov_b32_e32 v8, v21
	v_pk_mul_f32 v[4:5], v[0:1], v[4:5] op_sel_hi:[0,1]
	v_pk_mul_f32 v[6:7], v[0:1], v[6:7] op_sel_hi:[0,1]
	v_pk_mul_f32 v[12:13], v[0:1], v[12:13] op_sel_hi:[0,1]
	v_pk_mul_f32 v[8:9], v[0:1], v[8:9] op_sel_hi:[0,1]
	s_waitcnt lgkmcnt(1)
	v_pk_mul_f32 v[4:5], v[4:5], v[16:17]
	v_pk_mul_f32 v[6:7], v[6:7], v[18:19]
	s_waitcnt lgkmcnt(0)
	v_pk_mul_f32 v[12:13], v[12:13], v[22:23]
	v_pk_mul_f32 v[8:9], v[8:9], v[24:25]
	v_cvt_pk_bf16_f32 v4, v4, v5
	v_cvt_pk_bf16_f32 v5, v6, v7
	v_cvt_pk_bf16_f32 v6, v12, v13
	v_cvt_pk_bf16_f32 v7, v8, v9
	global_store_dwordx4 v[46:47], v[4:7], off offset:80
	ds_read_b128 v[4:7], v204 offset:192
	s_nop 0
	ds_read_b128 v[16:19], v204 offset:208
	v_mov_b32_e32 v8, v40
	v_mov_b32_e32 v9, v38
	v_mov_b32_e32 v12, v44
	v_mov_b32_e32 v13, v42
	v_pk_mul_f32 v[8:9], v[0:1], v[8:9] op_sel_hi:[0,1]
	v_pk_mul_f32 v[12:13], v[0:1], v[12:13] op_sel_hi:[0,1]
	v_mov_b32_e32 v38, v41
	v_mov_b32_e32 v42, v45
	s_waitcnt lgkmcnt(1)
	v_pk_mul_f32 v[4:5], v[10:11], v[4:5]
	v_pk_mul_f32 v[6:7], v[14:15], v[6:7]
	s_waitcnt lgkmcnt(0)
	v_pk_mul_f32 v[8:9], v[8:9], v[16:17]
	v_pk_mul_f32 v[10:11], v[12:13], v[18:19]
	v_cvt_pk_bf16_f32 v4, v4, v5
	v_cvt_pk_bf16_f32 v5, v6, v7
	v_cvt_pk_bf16_f32 v6, v8, v9
	v_cvt_pk_bf16_f32 v7, v10, v11
	global_store_dwordx4 v[46:47], v[4:7], off offset:96
	ds_read_b128 v[4:7], v204 offset:224
	s_nop 0
	ds_read_b128 v[8:11], v204 offset:240
	v_pk_mul_f32 v[12:13], v[0:1], v[38:39] op_sel_hi:[0,1]
	v_pk_mul_f32 v[14:15], v[0:1], v[146:147] op_sel_hi:[0,1]
	v_pk_mul_f32 v[16:17], v[0:1], v[42:43] op_sel_hi:[0,1]
	s_waitcnt lgkmcnt(1)
	v_pk_mul_f32 v[4:5], v[12:13], v[4:5]
	v_pk_mul_f32 v[6:7], v[14:15], v[6:7]
	s_waitcnt lgkmcnt(0)
	v_pk_mul_f32 v[8:9], v[16:17], v[8:9]
	v_pk_mul_f32 v[10:11], v[2:3], v[10:11]
	v_cvt_pk_bf16_f32 v2, v4, v5
	v_cvt_pk_bf16_f32 v3, v6, v7
	v_cvt_pk_bf16_f32 v4, v8, v9
	v_cvt_pk_bf16_f32 v5, v10, v11
	global_store_dwordx4 v[46:47], v[2:5], off offset:112
